# v83 + sample-tail small_gemm K sections with coalesced loads and a per-wave LDS transpose (same MFMA K sets and order)
# speedup vs baseline: 1.0106x; 1.0046x over previous
; template <class F>
; DI void small_gemm(LAS unsigned char* lds, const bf16_t* A, int lda, const bf16_t* Wt, int ldb, int K, int N, int tile0, int tstride, F f) {
;     ...
;         const bf16_t* ap = A + (size_t)r * lda + wid * kw + 8 * h;
;         const bf16_t* bp = Wt + (size_t)(n0 + r) * ldb + wid * kw + 8 * h;
; #pragma unroll 8
;         for (int ks = 0; ks < kw; ks += 16) {
;             const bf16x8 a = *(const bf16x8*)(ap + ks), b = *(const bf16x8*)(bp + ks);
;             acc = __builtin_amdgcn_mfma_f32_32x32x16_bf16(a, b, acc, 0, 0, 0);
;         }
; #pragma unroll
;         for (int i = 0; i < 16; ++i) red[wid * 1024 + i * 64 + lane] = acc[i];
;         __syncthreads();
.LBB0_816:
	v_and_b32_e32 v167, 63, v226
	v_lshrrev_b32_e32 v168, 4, v167
	v_and_b32_e32 v164, 15, v167
	v_lshlrev_b32_e32 v164, 4, v164
	v_mul_u32_u24_e32 v165, 0x110, v168
	v_add_u32_e32 v165, v165, v164
	v_lshl_or_b32 v164, v168, 12, v164
	v_lshrrev_b32_e32 v168, 6, v226
	v_and_b32_e32 v166, 31, v167
	v_mul_u32_u24_e32 v166, 0x110, v166
	v_lshrrev_b32_e32 v167, 5, v167
	v_lshl_add_u32 v166, v167, 4, v166
	s_nop 1
	v_readfirstlane_b32 s60, v168
	v_readfirstlane_b32 s56, v28
	v_readfirstlane_b32 s57, v29
	v_readfirstlane_b32 s58, v26
	v_readfirstlane_b32 s59, v27
	s_nop 4
	s_mul_i32 s60, s60, 0x4400
	s_sub_u32 s56, s56, 0x80
	s_subb_u32 s57, s57, 0
	s_sub_u32 s58, s58, 0x80
	s_subb_u32 s59, s59, 0
	v_add_u32_e32 v165, s60, v165
	v_add_u32_e32 v166, s60, v166
	global_load_dwordx4 v[32:35], v164, s[56:57]
	global_load_dwordx4 v[36:39], v164, s[58:59]
	s_add_u32 s56, s56, 0x4000
	s_addc_u32 s57, s57, 0
	s_add_u32 s58, s58, 0x4000
	s_addc_u32 s59, s59, 0
	global_load_dwordx4 v[40:43], v164, s[56:57]
	global_load_dwordx4 v[44:47], v164, s[58:59]
	s_add_u32 s56, s56, 0x4000
	s_addc_u32 s57, s57, 0
	s_add_u32 s58, s58, 0x4000
	s_addc_u32 s59, s59, 0
	global_load_dwordx4 v[48:51], v164, s[56:57]
	global_load_dwordx4 v[52:55], v164, s[58:59]
	s_add_u32 s56, s56, 0x4000
	s_addc_u32 s57, s57, 0
	s_add_u32 s58, s58, 0x4000
	s_addc_u32 s59, s59, 0
	global_load_dwordx4 v[56:59], v164, s[56:57]
	global_load_dwordx4 v[60:63], v164, s[58:59]
	s_add_u32 s56, s56, 0x4000
	s_addc_u32 s57, s57, 0
	s_add_u32 s58, s58, 0x4000
	s_addc_u32 s59, s59, 0
	global_load_dwordx4 v[64:67], v164, s[56:57]
	global_load_dwordx4 v[68:71], v164, s[58:59]
	s_add_u32 s56, s56, 0x4000
	s_addc_u32 s57, s57, 0
	s_add_u32 s58, s58, 0x4000
	s_addc_u32 s59, s59, 0
	global_load_dwordx4 v[72:75], v164, s[56:57]
	global_load_dwordx4 v[76:79], v164, s[58:59]
	s_add_u32 s56, s56, 0x4000
	s_addc_u32 s57, s57, 0
	s_add_u32 s58, s58, 0x4000
	s_addc_u32 s59, s59, 0
	global_load_dwordx4 v[80:83], v164, s[56:57]
	global_load_dwordx4 v[84:87], v164, s[58:59]
	s_add_u32 s56, s56, 0x4000
	s_addc_u32 s57, s57, 0
	s_add_u32 s58, s58, 0x4000
	s_addc_u32 s59, s59, 0
	global_load_dwordx4 v[88:91], v164, s[56:57]
	global_load_dwordx4 v[92:95], v164, s[58:59]
	s_sub_u32 s56, s56, 0x1c000
	s_subb_u32 s57, s57, 0
	s_sub_u32 s58, s58, 0x1c000
	s_subb_u32 s59, s59, 0
	global_load_dwordx4 v[96:99], v164, s[56:57] offset:256
	global_load_dwordx4 v[100:103], v164, s[58:59] offset:256
	s_add_u32 s56, s56, 0x4000
	s_addc_u32 s57, s57, 0
	s_add_u32 s58, s58, 0x4000
	s_addc_u32 s59, s59, 0
	global_load_dwordx4 v[104:107], v164, s[56:57] offset:256
	global_load_dwordx4 v[108:111], v164, s[58:59] offset:256
	s_add_u32 s56, s56, 0x4000
	s_addc_u32 s57, s57, 0
	s_add_u32 s58, s58, 0x4000
	s_addc_u32 s59, s59, 0
	global_load_dwordx4 v[112:115], v164, s[56:57] offset:256
	global_load_dwordx4 v[116:119], v164, s[58:59] offset:256
	s_add_u32 s56, s56, 0x4000
	s_addc_u32 s57, s57, 0
	s_add_u32 s58, s58, 0x4000
	s_addc_u32 s59, s59, 0
	global_load_dwordx4 v[120:123], v164, s[56:57] offset:256
	global_load_dwordx4 v[124:127], v164, s[58:59] offset:256
	s_add_u32 s56, s56, 0x4000
	s_addc_u32 s57, s57, 0
	s_add_u32 s58, s58, 0x4000
	s_addc_u32 s59, s59, 0
	global_load_dwordx4 v[132:135], v164, s[56:57] offset:256
	global_load_dwordx4 v[136:139], v164, s[58:59] offset:256
	s_add_u32 s56, s56, 0x4000
	s_addc_u32 s57, s57, 0
	s_add_u32 s58, s58, 0x4000
	s_addc_u32 s59, s59, 0
	global_load_dwordx4 v[140:143], v164, s[56:57] offset:256
	global_load_dwordx4 v[144:147], v164, s[58:59] offset:256
	s_add_u32 s56, s56, 0x4000
	s_addc_u32 s57, s57, 0
	s_add_u32 s58, s58, 0x4000
	s_addc_u32 s59, s59, 0
	global_load_dwordx4 v[148:151], v164, s[56:57] offset:256
	global_load_dwordx4 v[152:155], v164, s[58:59] offset:256
	s_add_u32 s56, s56, 0x4000
	s_addc_u32 s57, s57, 0
	s_add_u32 s58, s58, 0x4000
	s_addc_u32 s59, s59, 0
	global_load_dwordx4 v[156:159], v164, s[56:57] offset:256
	global_load_dwordx4 v[160:163], v164, s[58:59] offset:256
	s_waitcnt vmcnt(16)
	ds_write_b128 v165, v[32:35]
	ds_write_b128 v165, v[36:39] offset:8704
	ds_write_b128 v165, v[40:43] offset:1088
	ds_write_b128 v165, v[44:47] offset:9792
	ds_write_b128 v165, v[48:51] offset:2176
	ds_write_b128 v165, v[52:55] offset:10880
	ds_write_b128 v165, v[56:59] offset:3264
	ds_write_b128 v165, v[60:63] offset:11968
	ds_write_b128 v165, v[64:67] offset:4352
	ds_write_b128 v165, v[68:71] offset:13056
	ds_write_b128 v165, v[72:75] offset:5440
	ds_write_b128 v165, v[76:79] offset:14144
	ds_write_b128 v165, v[80:83] offset:6528
	ds_write_b128 v165, v[84:87] offset:15232
	ds_write_b128 v165, v[88:91] offset:7616
	ds_write_b128 v165, v[92:95] offset:16320
	s_waitcnt lgkmcnt(0)
; template <class F>
; DI void small_gemm(LAS unsigned char* lds, const bf16_t* A, int lda, const bf16_t* Wt, int ldb, int K, int N, int tile0, int tstride, F f) {
;     ...
;         for (int ks = 0; ks < kw; ks += 16) {
;             const bf16x8 a = *(const bf16x8*)(ap + ks), b = *(const bf16x8*)(bp + ks);
;             acc = __builtin_amdgcn_mfma_f32_32x32x16_bf16(a, b, acc, 0, 0, 0);
;         }
; #pragma unroll
;         for (int i = 0; i < 16; ++i) red[wid * 1024 + i * 64 + lane] = acc[i];
;         __syncthreads();
	ds_read_b128 v[180:183], v166
	ds_read_b128 v[184:187], v166 offset:8704
	ds_read_b128 v[188:191], v166 offset:32
	ds_read_b128 v[192:195], v166 offset:8736
	ds_read_b128 v[196:199], v166 offset:64
	ds_read_b128 v[200:203], v166 offset:8768
	ds_read_b128 v[204:207], v166 offset:96
	ds_read_b128 v[208:211], v166 offset:8800
	ds_read_b128 v[212:215], v166 offset:128
	ds_read_b128 v[216:219], v166 offset:8832
	ds_read_b128 v[220:223], v166 offset:160
	ds_read_b128 v[228:231], v166 offset:8864
	ds_read_b128 v[232:235], v166 offset:192
	ds_read_b128 v[236:239], v166 offset:8896
	ds_read_b128 v[240:243], v166 offset:224
	ds_read_b128 v[244:247], v166 offset:8928
	s_waitcnt lgkmcnt(14)
	v_mfma_f32_32x32x16_bf16 v[0:15], v[180:183], v[184:187], v[0:15]
	s_waitcnt lgkmcnt(12)
	v_mfma_f32_32x32x16_bf16 v[0:15], v[188:191], v[192:195], v[0:15]
	s_waitcnt lgkmcnt(10)
	v_mfma_f32_32x32x16_bf16 v[0:15], v[196:199], v[200:203], v[0:15]
	s_waitcnt lgkmcnt(8)
	v_mfma_f32_32x32x16_bf16 v[0:15], v[204:207], v[208:211], v[0:15]
	s_waitcnt lgkmcnt(6)
	v_mfma_f32_32x32x16_bf16 v[0:15], v[212:215], v[216:219], v[0:15]
	s_waitcnt lgkmcnt(4)
	v_mfma_f32_32x32x16_bf16 v[0:15], v[220:223], v[228:231], v[0:15]
	s_waitcnt lgkmcnt(2)
	v_mfma_f32_32x32x16_bf16 v[0:15], v[232:235], v[236:239], v[0:15]
	s_waitcnt lgkmcnt(0)
	v_mfma_f32_32x32x16_bf16 v[0:15], v[240:243], v[244:247], v[0:15]
	s_waitcnt vmcnt(0)
	ds_write_b128 v165, v[96:99]
	ds_write_b128 v165, v[100:103] offset:8704
	ds_write_b128 v165, v[104:107] offset:1088
	ds_write_b128 v165, v[108:111] offset:9792
	ds_write_b128 v165, v[112:115] offset:2176
	ds_write_b128 v165, v[116:119] offset:10880
	ds_write_b128 v165, v[120:123] offset:3264
	ds_write_b128 v165, v[124:127] offset:11968
	ds_write_b128 v165, v[132:135] offset:4352
	ds_write_b128 v165, v[136:139] offset:13056
	ds_write_b128 v165, v[140:143] offset:5440
	ds_write_b128 v165, v[144:147] offset:14144
	ds_write_b128 v165, v[148:151] offset:6528
	ds_write_b128 v165, v[152:155] offset:15232
	ds_write_b128 v165, v[156:159] offset:7616
	ds_write_b128 v165, v[160:163] offset:16320
	s_waitcnt lgkmcnt(0)
	ds_read_b128 v[180:183], v166
	ds_read_b128 v[184:187], v166 offset:8704
	ds_read_b128 v[188:191], v166 offset:32
	ds_read_b128 v[192:195], v166 offset:8736
	ds_read_b128 v[196:199], v166 offset:64
	ds_read_b128 v[200:203], v166 offset:8768
	ds_read_b128 v[204:207], v166 offset:96
	ds_read_b128 v[208:211], v166 offset:8800
	ds_read_b128 v[212:215], v166 offset:128
	ds_read_b128 v[216:219], v166 offset:8832
	ds_read_b128 v[220:223], v166 offset:160
	ds_read_b128 v[228:231], v166 offset:8864
	ds_read_b128 v[232:235], v166 offset:192
	ds_read_b128 v[236:239], v166 offset:8896
	ds_read_b128 v[240:243], v166 offset:224
	ds_read_b128 v[244:247], v166 offset:8928
	s_waitcnt lgkmcnt(14)
	v_mfma_f32_32x32x16_bf16 v[0:15], v[180:183], v[184:187], v[0:15]
	s_waitcnt lgkmcnt(12)
	v_mfma_f32_32x32x16_bf16 v[0:15], v[188:191], v[192:195], v[0:15]
	s_waitcnt lgkmcnt(10)
	v_mfma_f32_32x32x16_bf16 v[0:15], v[196:199], v[200:203], v[0:15]
	s_waitcnt lgkmcnt(8)
	v_mfma_f32_32x32x16_bf16 v[0:15], v[204:207], v[208:211], v[0:15]
	s_waitcnt lgkmcnt(6)
	v_mfma_f32_32x32x16_bf16 v[0:15], v[212:215], v[216:219], v[0:15]
	s_waitcnt lgkmcnt(4)
	v_mfma_f32_32x32x16_bf16 v[0:15], v[220:223], v[228:231], v[0:15]
	s_waitcnt lgkmcnt(2)
	v_mfma_f32_32x32x16_bf16 v[0:15], v[232:235], v[236:239], v[0:15]
	s_waitcnt lgkmcnt(0)
	v_mfma_f32_32x32x16_bf16 v[0:15], v[240:243], v[244:247], v[0:15]
	s_barrier
	s_nop 10
	ds_write2st64_b32 v31, v0, v1 offset1:1
	ds_write2st64_b32 v31, v2, v3 offset0:2 offset1:3
	ds_write2st64_b32 v31, v4, v5 offset0:4 offset1:5
	ds_write2st64_b32 v31, v6, v7 offset0:6 offset1:7
	ds_write2st64_b32 v31, v8, v9 offset0:8 offset1:9
	ds_write2st64_b32 v31, v10, v11 offset0:10 offset1:11
	ds_write2st64_b32 v31, v12, v13 offset0:12 offset1:13
	ds_write2st64_b32 v31, v14, v15 offset0:14 offset1:15
	s_waitcnt lgkmcnt(0)
	s_barrier
	s_and_saveexec_b64 s[10:11], s[6:7]
	s_cbranch_execz .LBB0_814
	v_lshl_or_b32 v0, s40, 5, v30
	v_ashrrev_i32_e32 v1, 31, v0
	v_lshl_add_u64 v[2:3], v[0:1], 1, s[0:1]
	s_mov_b64 s[14:15], 0
	v_mov_b32_e32 v4, v22
	v_mov_b32_e32 v5, v17

; template <class F>
; DI void small_gemm(LAS unsigned char* lds, const bf16_t* A, int lda, const bf16_t* Wt, int ldb, int K, int N, int tile0, int tstride, F f) {
;     ...
;         const bf16_t* ap = A + (size_t)r * lda + wid * kw + 8 * h;
;         const bf16_t* bp = Wt + (size_t)(n0 + r) * ldb + wid * kw + 8 * h;
; #pragma unroll 8
;         for (int ks = 0; ks < kw; ks += 16) {
;             const bf16x8 a = *(const bf16x8*)(ap + ks), b = *(const bf16x8*)(bp + ks);
;             acc = __builtin_amdgcn_mfma_f32_32x32x16_bf16(a, b, acc, 0, 0, 0);
;         }
; #pragma unroll
;         for (int i = 0; i < 16; ++i) red[wid * 1024 + i * 64 + lane] = acc[i];
;         __syncthreads();
.LBB0_2242:
	v_and_b32_e32 v167, 63, v226
	v_lshrrev_b32_e32 v168, 4, v167
	v_and_b32_e32 v164, 15, v167
	v_lshlrev_b32_e32 v164, 4, v164
	v_mul_u32_u24_e32 v165, 0x110, v168
	v_add_u32_e32 v165, v165, v164
	v_lshl_or_b32 v164, v168, 12, v164
	v_lshrrev_b32_e32 v168, 6, v226
	v_and_b32_e32 v166, 31, v167
	v_mul_u32_u24_e32 v166, 0x110, v166
	v_lshrrev_b32_e32 v167, 5, v167
	v_lshl_add_u32 v166, v167, 4, v166
	s_nop 1
	v_readfirstlane_b32 s60, v168
	v_readfirstlane_b32 s56, v28
	v_readfirstlane_b32 s57, v29
	v_readfirstlane_b32 s58, v26
	v_readfirstlane_b32 s59, v27
	s_nop 4
	s_mul_i32 s60, s60, 0x4400
	s_sub_u32 s56, s56, 0x80
	s_subb_u32 s57, s57, 0
	s_sub_u32 s58, s58, 0x80
	s_subb_u32 s59, s59, 0
	v_add_u32_e32 v165, s60, v165
	v_add_u32_e32 v166, s60, v166
	global_load_dwordx4 v[32:35], v164, s[56:57]
	global_load_dwordx4 v[36:39], v164, s[58:59]
	s_add_u32 s56, s56, 0x4000
	s_addc_u32 s57, s57, 0
	s_add_u32 s58, s58, 0x4000
	s_addc_u32 s59, s59, 0
	global_load_dwordx4 v[40:43], v164, s[56:57]
	global_load_dwordx4 v[44:47], v164, s[58:59]
	s_add_u32 s56, s56, 0x4000
	s_addc_u32 s57, s57, 0
	s_add_u32 s58, s58, 0x4000
	s_addc_u32 s59, s59, 0
	global_load_dwordx4 v[48:51], v164, s[56:57]
	global_load_dwordx4 v[52:55], v164, s[58:59]
	s_add_u32 s56, s56, 0x4000
	s_addc_u32 s57, s57, 0
	s_add_u32 s58, s58, 0x4000
	s_addc_u32 s59, s59, 0
	global_load_dwordx4 v[56:59], v164, s[56:57]
	global_load_dwordx4 v[60:63], v164, s[58:59]
	s_add_u32 s56, s56, 0x4000
	s_addc_u32 s57, s57, 0
	s_add_u32 s58, s58, 0x4000
	s_addc_u32 s59, s59, 0
	global_load_dwordx4 v[64:67], v164, s[56:57]
	global_load_dwordx4 v[68:71], v164, s[58:59]
	s_add_u32 s56, s56, 0x4000
	s_addc_u32 s57, s57, 0
	s_add_u32 s58, s58, 0x4000
	s_addc_u32 s59, s59, 0
	global_load_dwordx4 v[72:75], v164, s[56:57]
	global_load_dwordx4 v[76:79], v164, s[58:59]
	s_add_u32 s56, s56, 0x4000
	s_addc_u32 s57, s57, 0
	s_add_u32 s58, s58, 0x4000
	s_addc_u32 s59, s59, 0
	global_load_dwordx4 v[80:83], v164, s[56:57]
	global_load_dwordx4 v[84:87], v164, s[58:59]
	s_add_u32 s56, s56, 0x4000
	s_addc_u32 s57, s57, 0
	s_add_u32 s58, s58, 0x4000
	s_addc_u32 s59, s59, 0
	global_load_dwordx4 v[88:91], v164, s[56:57]
	global_load_dwordx4 v[92:95], v164, s[58:59]
	s_sub_u32 s56, s56, 0x1c000
	s_subb_u32 s57, s57, 0
	s_sub_u32 s58, s58, 0x1c000
	s_subb_u32 s59, s59, 0
	global_load_dwordx4 v[96:99], v164, s[56:57] offset:256
	global_load_dwordx4 v[100:103], v164, s[58:59] offset:256
	s_add_u32 s56, s56, 0x4000
	s_addc_u32 s57, s57, 0
	s_add_u32 s58, s58, 0x4000
	s_addc_u32 s59, s59, 0
	global_load_dwordx4 v[104:107], v164, s[56:57] offset:256
	global_load_dwordx4 v[108:111], v164, s[58:59] offset:256
	s_add_u32 s56, s56, 0x4000
	s_addc_u32 s57, s57, 0
	s_add_u32 s58, s58, 0x4000
	s_addc_u32 s59, s59, 0
	global_load_dwordx4 v[112:115], v164, s[56:57] offset:256
	global_load_dwordx4 v[116:119], v164, s[58:59] offset:256
	s_add_u32 s56, s56, 0x4000
	s_addc_u32 s57, s57, 0
	s_add_u32 s58, s58, 0x4000
	s_addc_u32 s59, s59, 0
	global_load_dwordx4 v[120:123], v164, s[56:57] offset:256
	global_load_dwordx4 v[124:127], v164, s[58:59] offset:256
	s_add_u32 s56, s56, 0x4000
	s_addc_u32 s57, s57, 0
	s_add_u32 s58, s58, 0x4000
	s_addc_u32 s59, s59, 0
	global_load_dwordx4 v[132:135], v164, s[56:57] offset:256
	global_load_dwordx4 v[136:139], v164, s[58:59] offset:256
	s_add_u32 s56, s56, 0x4000
	s_addc_u32 s57, s57, 0
	s_add_u32 s58, s58, 0x4000
	s_addc_u32 s59, s59, 0
	global_load_dwordx4 v[140:143], v164, s[56:57] offset:256
	global_load_dwordx4 v[144:147], v164, s[58:59] offset:256
	s_add_u32 s56, s56, 0x4000
	s_addc_u32 s57, s57, 0
	s_add_u32 s58, s58, 0x4000
	s_addc_u32 s59, s59, 0
	global_load_dwordx4 v[148:151], v164, s[56:57] offset:256
	global_load_dwordx4 v[152:155], v164, s[58:59] offset:256
	s_add_u32 s56, s56, 0x4000
	s_addc_u32 s57, s57, 0
	s_add_u32 s58, s58, 0x4000
	s_addc_u32 s59, s59, 0
	global_load_dwordx4 v[156:159], v164, s[56:57] offset:256
	global_load_dwordx4 v[160:163], v164, s[58:59] offset:256
	s_waitcnt vmcnt(16)
	ds_write_b128 v165, v[32:35]
	ds_write_b128 v165, v[36:39] offset:8704
	ds_write_b128 v165, v[40:43] offset:1088
	ds_write_b128 v165, v[44:47] offset:9792
	ds_write_b128 v165, v[48:51] offset:2176
	ds_write_b128 v165, v[52:55] offset:10880
	ds_write_b128 v165, v[56:59] offset:3264
	ds_write_b128 v165, v[60:63] offset:11968
	ds_write_b128 v165, v[64:67] offset:4352
	ds_write_b128 v165, v[68:71] offset:13056
	ds_write_b128 v165, v[72:75] offset:5440
	ds_write_b128 v165, v[76:79] offset:14144
	ds_write_b128 v165, v[80:83] offset:6528
	ds_write_b128 v165, v[84:87] offset:15232
	ds_write_b128 v165, v[88:91] offset:7616
	ds_write_b128 v165, v[92:95] offset:16320
	s_waitcnt lgkmcnt(0)
; template <class F>
; DI void small_gemm(LAS unsigned char* lds, const bf16_t* A, int lda, const bf16_t* Wt, int ldb, int K, int N, int tile0, int tstride, F f) {
;     ...
;         for (int ks = 0; ks < kw; ks += 16) {
;             const bf16x8 a = *(const bf16x8*)(ap + ks), b = *(const bf16x8*)(bp + ks);
;             acc = __builtin_amdgcn_mfma_f32_32x32x16_bf16(a, b, acc, 0, 0, 0);
;         }
; #pragma unroll
;         for (int i = 0; i < 16; ++i) red[wid * 1024 + i * 64 + lane] = acc[i];
;         __syncthreads();
	ds_read_b128 v[180:183], v166
	ds_read_b128 v[184:187], v166 offset:8704
	ds_read_b128 v[188:191], v166 offset:32
	ds_read_b128 v[192:195], v166 offset:8736
	ds_read_b128 v[196:199], v166 offset:64
	ds_read_b128 v[200:203], v166 offset:8768
	ds_read_b128 v[204:207], v166 offset:96
	ds_read_b128 v[208:211], v166 offset:8800
	ds_read_b128 v[212:215], v166 offset:128
	ds_read_b128 v[216:219], v166 offset:8832
	ds_read_b128 v[220:223], v166 offset:160
	ds_read_b128 v[228:231], v166 offset:8864
	ds_read_b128 v[232:235], v166 offset:192
	ds_read_b128 v[236:239], v166 offset:8896
	ds_read_b128 v[240:243], v166 offset:224
	ds_read_b128 v[244:247], v166 offset:8928
	s_waitcnt lgkmcnt(14)
	v_mfma_f32_32x32x16_bf16 v[0:15], v[180:183], v[184:187], v[0:15]
	s_waitcnt lgkmcnt(12)
	v_mfma_f32_32x32x16_bf16 v[0:15], v[188:191], v[192:195], v[0:15]
	s_waitcnt lgkmcnt(10)
	v_mfma_f32_32x32x16_bf16 v[0:15], v[196:199], v[200:203], v[0:15]
	s_waitcnt lgkmcnt(8)
	v_mfma_f32_32x32x16_bf16 v[0:15], v[204:207], v[208:211], v[0:15]
	s_waitcnt lgkmcnt(6)
	v_mfma_f32_32x32x16_bf16 v[0:15], v[212:215], v[216:219], v[0:15]
	s_waitcnt lgkmcnt(4)
	v_mfma_f32_32x32x16_bf16 v[0:15], v[220:223], v[228:231], v[0:15]
	s_waitcnt lgkmcnt(2)
	v_mfma_f32_32x32x16_bf16 v[0:15], v[232:235], v[236:239], v[0:15]
	s_waitcnt lgkmcnt(0)
	v_mfma_f32_32x32x16_bf16 v[0:15], v[240:243], v[244:247], v[0:15]
	s_waitcnt vmcnt(0)
	ds_write_b128 v165, v[96:99]
	ds_write_b128 v165, v[100:103] offset:8704
	ds_write_b128 v165, v[104:107] offset:1088
	ds_write_b128 v165, v[108:111] offset:9792
	ds_write_b128 v165, v[112:115] offset:2176
	ds_write_b128 v165, v[116:119] offset:10880
	ds_write_b128 v165, v[120:123] offset:3264
	ds_write_b128 v165, v[124:127] offset:11968
	ds_write_b128 v165, v[132:135] offset:4352
	ds_write_b128 v165, v[136:139] offset:13056
	ds_write_b128 v165, v[140:143] offset:5440
	ds_write_b128 v165, v[144:147] offset:14144
	ds_write_b128 v165, v[148:151] offset:6528
	ds_write_b128 v165, v[152:155] offset:15232
	ds_write_b128 v165, v[156:159] offset:7616
	ds_write_b128 v165, v[160:163] offset:16320
	s_waitcnt lgkmcnt(0)
	ds_read_b128 v[180:183], v166
	ds_read_b128 v[184:187], v166 offset:8704
	ds_read_b128 v[188:191], v166 offset:32
	ds_read_b128 v[192:195], v166 offset:8736
	ds_read_b128 v[196:199], v166 offset:64
	ds_read_b128 v[200:203], v166 offset:8768
	ds_read_b128 v[204:207], v166 offset:96
	ds_read_b128 v[208:211], v166 offset:8800
	ds_read_b128 v[212:215], v166 offset:128
	ds_read_b128 v[216:219], v166 offset:8832
	ds_read_b128 v[220:223], v166 offset:160
	ds_read_b128 v[228:231], v166 offset:8864
	ds_read_b128 v[232:235], v166 offset:192
	ds_read_b128 v[236:239], v166 offset:8896
	ds_read_b128 v[240:243], v166 offset:224
	ds_read_b128 v[244:247], v166 offset:8928
	s_waitcnt lgkmcnt(14)
	v_mfma_f32_32x32x16_bf16 v[0:15], v[180:183], v[184:187], v[0:15]
	s_waitcnt lgkmcnt(12)
	v_mfma_f32_32x32x16_bf16 v[0:15], v[188:191], v[192:195], v[0:15]
	s_waitcnt lgkmcnt(10)
	v_mfma_f32_32x32x16_bf16 v[0:15], v[196:199], v[200:203], v[0:15]
	s_waitcnt lgkmcnt(8)
	v_mfma_f32_32x32x16_bf16 v[0:15], v[204:207], v[208:211], v[0:15]
	s_waitcnt lgkmcnt(6)
	v_mfma_f32_32x32x16_bf16 v[0:15], v[212:215], v[216:219], v[0:15]
	s_waitcnt lgkmcnt(4)
	v_mfma_f32_32x32x16_bf16 v[0:15], v[220:223], v[228:231], v[0:15]
	s_waitcnt lgkmcnt(2)
	v_mfma_f32_32x32x16_bf16 v[0:15], v[232:235], v[236:239], v[0:15]
	s_waitcnt lgkmcnt(0)
	v_mfma_f32_32x32x16_bf16 v[0:15], v[240:243], v[244:247], v[0:15]
	s_barrier
	s_nop 10
	ds_write2st64_b32 v30, v0, v1 offset1:1
	ds_write2st64_b32 v30, v2, v3 offset0:2 offset1:3
	ds_write2st64_b32 v30, v4, v5 offset0:4 offset1:5
	ds_write2st64_b32 v30, v6, v7 offset0:6 offset1:7
	ds_write2st64_b32 v30, v8, v9 offset0:8 offset1:9
	ds_write2st64_b32 v30, v10, v11 offset0:10 offset1:11
	ds_write2st64_b32 v30, v12, v13 offset0:12 offset1:13
	ds_write2st64_b32 v30, v14, v15 offset0:14 offset1:15
	s_waitcnt lgkmcnt(0)
	s_barrier
	s_and_saveexec_b64 s[8:9], s[0:1]
	s_cbranch_execz .LBB0_2240
	v_lshl_or_b32 v0, s16, 5, v17
	v_ashrrev_i32_e32 v1, 31, v0
	s_mov_b64 s[12:13], 0
	v_mov_b32_e32 v2, v22
	v_mov_b32_e32 v3, v226
